# P1 silu epilogue: packed scale/+1 with SGPR constant pairs, copies only on the no-activation path (28 instead of 48 VALU per 8 values)
# baseline (speedup 1.0000x reference)
; __device__ __forceinline__ unsigned cvt_pk_bf16(float lo, float hi) { unsigned r; asm volatile("v_cvt_pk_bf16_f32 %0, %1, %2" : "=v"(r) : "v"(lo), "v"(hi)); return r; }
; __device__ __forceinline__ float fast_sigmoid(float x) { return __builtin_amdgcn_rcpf(1.0f + __builtin_amdgcn_exp2f(-1.44269504089f * x)); }
; __device__ __forceinline__ float fast_silu(float x) { return x * fast_sigmoid(x); }
;     __device__ __forceinline__ void operator()(const f32x4 (&acc)[2][2][4][2], const Unit& u, int wr, int wc, int fr, int fq) const {
;     ...
;                 bf16_t* base = dst + (size_t)row0 * ldc + colt + cl;
; #pragma unroll
;                 for (int ai = 0; ai < 2; ++ai)
; #pragma unroll
;                     for (int m = 0; m < 4; ++m)
; #pragma unroll
;                         for (int bj = 0; bj < 2; ++bj) { f32x4 v0 = acc[ai][bj][m][0], v1 = acc[ai][bj][m][1];
;                             if (act) {
; #pragma unroll
;                                 for (int j = 0; j < 4; ++j) { v0[j] = fast_silu(v0[j]); v1[j] = fast_silu(v1[j]); } }
;                             u32x4 w; w.x = cvt_pk_bf16(v0[0], v0[1]); w.y = cvt_pk_bf16(v0[2], v0[3]); w.z = cvt_pk_bf16(v1[0], v1[1]); w.w = cvt_pk_bf16(v1[2], v1[3]);
;                             *(u32x4*)(base + (size_t)(ai * 128 + m * 16) * ldc + bj * 128) = w; }
.LBB0_224:
	s_mov_b32 s100, 0xbfb8aa3b
	s_mov_b32 s101, 0xbfb8aa3b
	s_mov_b32 s98, 1.0
	s_mov_b32 s99, 1.0
	v_cndmask_b32_e64 v138, 0, 1, s[72:73]
	v_cmp_ne_u32_e64 s[4:5], 1, v138
	s_andn2_b64 vcc, exec, s[72:73]
	s_cbranch_vccz .Lsilu_0
	v_mov_b32_e32 v150, v128
	v_mov_b32_e32 v151, v129
	v_mov_b32_e32 v152, v120
	v_mov_b32_e32 v153, v121
	v_mov_b32_e32 v154, v126
	v_mov_b32_e32 v155, v127
	v_mov_b32_e32 v156, v118
	v_mov_b32_e32 v157, v119
	s_branch .LBB0_226
.Lsilu_0:
	v_pk_mul_f32 v[150:151], v[128:129], s[100:101]
	v_pk_mul_f32 v[152:153], v[120:121], s[100:101]
	v_pk_mul_f32 v[154:155], v[126:127], s[100:101]
	v_pk_mul_f32 v[156:157], v[118:119], s[100:101]
	v_exp_f32_e32 v150, v150
	v_exp_f32_e32 v151, v151
	v_exp_f32_e32 v152, v152
	v_exp_f32_e32 v153, v153
	v_exp_f32_e32 v154, v154
	v_exp_f32_e32 v155, v155
	v_exp_f32_e32 v156, v156
	v_exp_f32_e32 v157, v157
	v_pk_add_f32 v[150:151], v[150:151], s[98:99]
	v_pk_add_f32 v[152:153], v[152:153], s[98:99]
	v_pk_add_f32 v[154:155], v[154:155], s[98:99]
	v_pk_add_f32 v[156:157], v[156:157], s[98:99]
	v_rcp_f32_e32 v150, v150
	v_rcp_f32_e32 v151, v151
	v_rcp_f32_e32 v152, v152
	v_rcp_f32_e32 v153, v153
	v_rcp_f32_e32 v154, v154
	v_rcp_f32_e32 v155, v155
	v_rcp_f32_e32 v156, v156
	v_rcp_f32_e32 v157, v157
	v_pk_mul_f32 v[150:151], v[128:129], v[150:151]
	v_pk_mul_f32 v[152:153], v[120:121], v[152:153]
	v_pk_mul_f32 v[154:155], v[126:127], v[154:155]
	v_pk_mul_f32 v[156:157], v[118:119], v[156:157]
.LBB0_226:
	v_ashrrev_i32_e32 v138, 31, v146
	v_mul_lo_u32 v147, s69, v146
	v_mul_lo_u32 v138, s68, v138
	v_mad_u64_u32 v[148:149], s[72:73], s68, v146, 0
	v_add3_u32 v149, v149, v138, v147
	v_lshl_add_u64 v[148:149], v[148:149], 1, s[70:71]
	s_ashr_i32 s67, s66, 31
	v_lshl_add_u64 v[148:149], s[66:67], 1, v[148:149]
	v_lshlrev_b32_e32 v138, 1, v140
	v_lshl_add_u64 v[148:149], v[148:149], 0, v[138:139]
	v_cvt_pk_bf16_f32 v154, v154, v155
	v_cvt_pk_bf16_f32 v155, v150, v151
	v_cvt_pk_bf16_f32 v156, v156, v157
	v_cvt_pk_bf16_f32 v157, v152, v153
	global_store_dwordx4 v[148:149], v[154:157], off
	s_and_b64 vcc, exec, s[4:5]
	s_cbranch_vccz .Lsilu_1
	v_mov_b32_e32 v150, v124
	v_mov_b32_e32 v151, v125
	v_mov_b32_e32 v152, v116
	v_mov_b32_e32 v153, v117
	v_mov_b32_e32 v154, v122
	v_mov_b32_e32 v155, v123
	v_mov_b32_e32 v156, v114
	v_mov_b32_e32 v157, v115
	s_branch .LBB0_228
.Lsilu_1:
	v_pk_mul_f32 v[150:151], v[124:125], s[100:101]
	v_pk_mul_f32 v[152:153], v[116:117], s[100:101]
	v_pk_mul_f32 v[154:155], v[122:123], s[100:101]
	v_pk_mul_f32 v[156:157], v[114:115], s[100:101]
	v_exp_f32_e32 v150, v150
	v_exp_f32_e32 v151, v151
	v_exp_f32_e32 v152, v152
	v_exp_f32_e32 v153, v153
	v_exp_f32_e32 v154, v154
	v_exp_f32_e32 v155, v155
	v_exp_f32_e32 v156, v156
	v_exp_f32_e32 v157, v157
	v_pk_add_f32 v[150:151], v[150:151], s[98:99]
	v_pk_add_f32 v[152:153], v[152:153], s[98:99]
	v_pk_add_f32 v[154:155], v[154:155], s[98:99]
	v_pk_add_f32 v[156:157], v[156:157], s[98:99]
	v_rcp_f32_e32 v150, v150
	v_rcp_f32_e32 v151, v151
	v_rcp_f32_e32 v152, v152
	v_rcp_f32_e32 v153, v153
	v_rcp_f32_e32 v154, v154
	v_rcp_f32_e32 v155, v155
	v_rcp_f32_e32 v156, v156
	v_rcp_f32_e32 v157, v157
	v_pk_mul_f32 v[150:151], v[124:125], v[150:151]
	v_pk_mul_f32 v[152:153], v[116:117], v[152:153]
	v_pk_mul_f32 v[154:155], v[122:123], v[154:155]
	v_pk_mul_f32 v[156:157], v[114:115], v[156:157]
.LBB0_228:
	v_cvt_pk_bf16_f32 v154, v154, v155
	v_cvt_pk_bf16_f32 v155, v150, v151
	s_nop 0
	v_cvt_pk_bf16_f32 v156, v156, v157
	v_cvt_pk_bf16_f32 v157, v152, v153
	global_store_dwordx4 v[148:149], v[154:157], off offset:256
	s_and_b64 vcc, exec, s[4:5]
	s_cbranch_vccz .Lsilu_2
	v_mov_b32_e32 v150, v112
	v_mov_b32_e32 v151, v113
	v_mov_b32_e32 v152, v104
	v_mov_b32_e32 v153, v105
	v_mov_b32_e32 v154, v110
	v_mov_b32_e32 v155, v111
	v_mov_b32_e32 v156, v102
	v_mov_b32_e32 v157, v103
	s_branch .LBB0_230
.Lsilu_2:
	v_pk_mul_f32 v[150:151], v[112:113], s[100:101]
	v_pk_mul_f32 v[152:153], v[104:105], s[100:101]
	v_pk_mul_f32 v[154:155], v[110:111], s[100:101]
	v_pk_mul_f32 v[156:157], v[102:103], s[100:101]
	v_exp_f32_e32 v150, v150
	v_exp_f32_e32 v151, v151
	v_exp_f32_e32 v152, v152
	v_exp_f32_e32 v153, v153
	v_exp_f32_e32 v154, v154
	v_exp_f32_e32 v155, v155
	v_exp_f32_e32 v156, v156
	v_exp_f32_e32 v157, v157
	v_pk_add_f32 v[150:151], v[150:151], s[98:99]
	v_pk_add_f32 v[152:153], v[152:153], s[98:99]
	v_pk_add_f32 v[154:155], v[154:155], s[98:99]
	v_pk_add_f32 v[156:157], v[156:157], s[98:99]
	v_rcp_f32_e32 v150, v150
	v_rcp_f32_e32 v151, v151
	v_rcp_f32_e32 v152, v152
	v_rcp_f32_e32 v153, v153
	v_rcp_f32_e32 v154, v154
	v_rcp_f32_e32 v155, v155
	v_rcp_f32_e32 v156, v156
	v_rcp_f32_e32 v157, v157
	v_pk_mul_f32 v[150:151], v[112:113], v[150:151]
	v_pk_mul_f32 v[152:153], v[104:105], v[152:153]
	v_pk_mul_f32 v[154:155], v[110:111], v[154:155]
	v_pk_mul_f32 v[156:157], v[102:103], v[156:157]
.LBB0_230:
	s_lshl_b64 s[66:67], s[68:69], 5
	v_lshl_add_u64 v[148:149], v[148:149], 0, s[66:67]
	v_cvt_pk_bf16_f32 v154, v154, v155
	v_cvt_pk_bf16_f32 v155, v150, v151
	v_cvt_pk_bf16_f32 v156, v156, v157
	v_cvt_pk_bf16_f32 v157, v152, v153
	global_store_dwordx4 v[148:149], v[154:157], off
	s_and_b64 vcc, exec, s[4:5]
	s_cbranch_vccz .Lsilu_3
	v_mov_b32_e32 v150, v108
	v_mov_b32_e32 v151, v109
	v_mov_b32_e32 v152, v100
	v_mov_b32_e32 v153, v101
	v_mov_b32_e32 v154, v106
	v_mov_b32_e32 v155, v107
	v_mov_b32_e32 v156, v98
	v_mov_b32_e32 v157, v99
	s_branch .LBB0_232
; __device__ __forceinline__ unsigned cvt_pk_bf16(float lo, float hi) { unsigned r; asm volatile("v_cvt_pk_bf16_f32 %0, %1, %2" : "=v"(r) : "v"(lo), "v"(hi)); return r; }
; __device__ __forceinline__ float fast_silu(float x) { return x * fast_sigmoid(x); }
;     __device__ __forceinline__ void operator()(const f32x4 (&acc)[2][2][4][2], const Unit& u, int wr, int wc, int fr, int fq) const {
;     ...
;                 bf16_t* base = dst + (size_t)row0 * ldc + colt + cl;
; #pragma unroll
;                 for (int ai = 0; ai < 2; ++ai)
; #pragma unroll
;                     for (int m = 0; m < 4; ++m)
; #pragma unroll
;                         for (int bj = 0; bj < 2; ++bj) { f32x4 v0 = acc[ai][bj][m][0], v1 = acc[ai][bj][m][1];
;                             if (act) {
; #pragma unroll
;                                 for (int j = 0; j < 4; ++j) { v0[j] = fast_silu(v0[j]); v1[j] = fast_silu(v1[j]); } }
;                             u32x4 w; w.x = cvt_pk_bf16(v0[0], v0[1]); w.y = cvt_pk_bf16(v0[2], v0[3]); w.z = cvt_pk_bf16(v1[0], v1[1]); w.w = cvt_pk_bf16(v1[2], v1[3]);
;                             *(u32x4*)(base + (size_t)(ai * 128 + m * 16) * ldc + bj * 128) = w; }
.Lsilu_3:
	v_pk_mul_f32 v[150:151], v[108:109], s[100:101]
	v_pk_mul_f32 v[152:153], v[100:101], s[100:101]
	v_pk_mul_f32 v[154:155], v[106:107], s[100:101]
	v_pk_mul_f32 v[156:157], v[98:99], s[100:101]
	v_exp_f32_e32 v150, v150
	v_exp_f32_e32 v151, v151
	v_exp_f32_e32 v152, v152
	v_exp_f32_e32 v153, v153
	v_exp_f32_e32 v154, v154
	v_exp_f32_e32 v155, v155
	v_exp_f32_e32 v156, v156
	v_exp_f32_e32 v157, v157
	v_pk_add_f32 v[150:151], v[150:151], s[98:99]
	v_pk_add_f32 v[152:153], v[152:153], s[98:99]
	v_pk_add_f32 v[154:155], v[154:155], s[98:99]
	v_pk_add_f32 v[156:157], v[156:157], s[98:99]
	v_rcp_f32_e32 v150, v150
	v_rcp_f32_e32 v151, v151
	v_rcp_f32_e32 v152, v152
	v_rcp_f32_e32 v153, v153
	v_rcp_f32_e32 v154, v154
	v_rcp_f32_e32 v155, v155
	v_rcp_f32_e32 v156, v156
	v_rcp_f32_e32 v157, v157
	v_pk_mul_f32 v[150:151], v[108:109], v[150:151]
	v_pk_mul_f32 v[152:153], v[100:101], v[152:153]
	v_pk_mul_f32 v[154:155], v[106:107], v[154:155]
	v_pk_mul_f32 v[156:157], v[98:99], v[156:157]
.LBB0_232:
	v_cvt_pk_bf16_f32 v154, v154, v155
	v_cvt_pk_bf16_f32 v155, v150, v151
	s_nop 0
	v_cvt_pk_bf16_f32 v156, v156, v157
	v_cvt_pk_bf16_f32 v157, v152, v153
	global_store_dwordx4 v[148:149], v[154:157], off offset:256
	s_and_b64 vcc, exec, s[4:5]
	s_cbranch_vccz .Lsilu_4
	v_mov_b32_e32 v150, v96
	v_mov_b32_e32 v151, v97
	v_mov_b32_e32 v152, v88
	v_mov_b32_e32 v153, v89
	v_mov_b32_e32 v154, v94
	v_mov_b32_e32 v155, v95
	v_mov_b32_e32 v156, v86
	v_mov_b32_e32 v157, v87
	s_branch .LBB0_234
.Lsilu_4:
	v_pk_mul_f32 v[150:151], v[96:97], s[100:101]
	v_pk_mul_f32 v[152:153], v[88:89], s[100:101]
	v_pk_mul_f32 v[154:155], v[94:95], s[100:101]
	v_pk_mul_f32 v[156:157], v[86:87], s[100:101]
	v_exp_f32_e32 v150, v150
	v_exp_f32_e32 v151, v151
	v_exp_f32_e32 v152, v152
	v_exp_f32_e32 v153, v153
	v_exp_f32_e32 v154, v154
	v_exp_f32_e32 v155, v155
	v_exp_f32_e32 v156, v156
	v_exp_f32_e32 v157, v157
	v_pk_add_f32 v[150:151], v[150:151], s[98:99]
	v_pk_add_f32 v[152:153], v[152:153], s[98:99]
	v_pk_add_f32 v[154:155], v[154:155], s[98:99]
	v_pk_add_f32 v[156:157], v[156:157], s[98:99]
	v_rcp_f32_e32 v150, v150
	v_rcp_f32_e32 v151, v151
	v_rcp_f32_e32 v152, v152
	v_rcp_f32_e32 v153, v153
	v_rcp_f32_e32 v154, v154
	v_rcp_f32_e32 v155, v155
	v_rcp_f32_e32 v156, v156
	v_rcp_f32_e32 v157, v157
	v_pk_mul_f32 v[150:151], v[96:97], v[150:151]
	v_pk_mul_f32 v[152:153], v[88:89], v[152:153]
	v_pk_mul_f32 v[154:155], v[94:95], v[154:155]
	v_pk_mul_f32 v[156:157], v[86:87], v[156:157]
.LBB0_234:
	v_lshl_add_u64 v[148:149], v[148:149], 0, s[66:67]
	v_cvt_pk_bf16_f32 v154, v154, v155
	v_cvt_pk_bf16_f32 v155, v150, v151
	v_cvt_pk_bf16_f32 v156, v156, v157
	v_cvt_pk_bf16_f32 v157, v152, v153
	global_store_dwordx4 v[148:149], v[154:157], off
	s_and_b64 vcc, exec, s[4:5]
	s_cbranch_vccz .Lsilu_5
	v_mov_b32_e32 v150, v92
	v_mov_b32_e32 v151, v93
	v_mov_b32_e32 v152, v84
	v_mov_b32_e32 v153, v85
	v_mov_b32_e32 v154, v90
	v_mov_b32_e32 v155, v91
	v_mov_b32_e32 v156, v82
	v_mov_b32_e32 v157, v83
	s_branch .LBB0_236
.Lsilu_5:
	v_pk_mul_f32 v[150:151], v[92:93], s[100:101]
	v_pk_mul_f32 v[152:153], v[84:85], s[100:101]
	v_pk_mul_f32 v[154:155], v[90:91], s[100:101]
	v_pk_mul_f32 v[156:157], v[82:83], s[100:101]
	v_exp_f32_e32 v150, v150
	v_exp_f32_e32 v151, v151
	v_exp_f32_e32 v152, v152
	v_exp_f32_e32 v153, v153
	v_exp_f32_e32 v154, v154
	v_exp_f32_e32 v155, v155
	v_exp_f32_e32 v156, v156
	v_exp_f32_e32 v157, v157
	v_pk_add_f32 v[150:151], v[150:151], s[98:99]
	v_pk_add_f32 v[152:153], v[152:153], s[98:99]
	v_pk_add_f32 v[154:155], v[154:155], s[98:99]
	v_pk_add_f32 v[156:157], v[156:157], s[98:99]
	v_rcp_f32_e32 v150, v150
	v_rcp_f32_e32 v151, v151
	v_rcp_f32_e32 v152, v152
	v_rcp_f32_e32 v153, v153
	v_rcp_f32_e32 v154, v154
	v_rcp_f32_e32 v155, v155
	v_rcp_f32_e32 v156, v156
	v_rcp_f32_e32 v157, v157
	v_pk_mul_f32 v[150:151], v[92:93], v[150:151]
	v_pk_mul_f32 v[152:153], v[84:85], v[152:153]
	v_pk_mul_f32 v[154:155], v[90:91], v[154:155]
	v_pk_mul_f32 v[156:157], v[82:83], v[156:157]
.LBB0_236:
	v_cvt_pk_bf16_f32 v154, v154, v155
	v_cvt_pk_bf16_f32 v155, v150, v151
	s_nop 0
	v_cvt_pk_bf16_f32 v156, v156, v157
	v_cvt_pk_bf16_f32 v157, v152, v153
	global_store_dwordx4 v[148:149], v[154:157], off offset:256
	s_and_b64 vcc, exec, s[4:5]
	s_cbranch_vccz .Lsilu_6
	v_mov_b32_e32 v150, v80
	v_mov_b32_e32 v151, v81
	v_mov_b32_e32 v152, v72
	v_mov_b32_e32 v153, v73
	v_mov_b32_e32 v154, v78
	v_mov_b32_e32 v155, v79
	v_mov_b32_e32 v156, v70
	v_mov_b32_e32 v157, v71
	s_branch .LBB0_238
.Lsilu_6:
	v_pk_mul_f32 v[150:151], v[80:81], s[100:101]
	v_pk_mul_f32 v[152:153], v[72:73], s[100:101]
	v_pk_mul_f32 v[154:155], v[78:79], s[100:101]
	v_pk_mul_f32 v[156:157], v[70:71], s[100:101]
	v_exp_f32_e32 v150, v150
	v_exp_f32_e32 v151, v151
	v_exp_f32_e32 v152, v152
	v_exp_f32_e32 v153, v153
	v_exp_f32_e32 v154, v154
	v_exp_f32_e32 v155, v155
	v_exp_f32_e32 v156, v156
	v_exp_f32_e32 v157, v157
	v_pk_add_f32 v[150:151], v[150:151], s[98:99]
	v_pk_add_f32 v[152:153], v[152:153], s[98:99]
	v_pk_add_f32 v[154:155], v[154:155], s[98:99]
	v_pk_add_f32 v[156:157], v[156:157], s[98:99]
	v_rcp_f32_e32 v150, v150
	v_rcp_f32_e32 v151, v151
	v_rcp_f32_e32 v152, v152
	v_rcp_f32_e32 v153, v153
	v_rcp_f32_e32 v154, v154
	v_rcp_f32_e32 v155, v155
	v_rcp_f32_e32 v156, v156
	v_rcp_f32_e32 v157, v157
	v_pk_mul_f32 v[150:151], v[80:81], v[150:151]
	v_pk_mul_f32 v[152:153], v[72:73], v[152:153]
	v_pk_mul_f32 v[154:155], v[78:79], v[154:155]
	v_pk_mul_f32 v[156:157], v[70:71], v[156:157]
; __device__ __forceinline__ unsigned cvt_pk_bf16(float lo, float hi) { unsigned r; asm volatile("v_cvt_pk_bf16_f32 %0, %1, %2" : "=v"(r) : "v"(lo), "v"(hi)); return r; }
; __device__ __forceinline__ float fast_silu(float x) { return x * fast_sigmoid(x); }
;     __device__ __forceinline__ void operator()(const f32x4 (&acc)[2][2][4][2], const Unit& u, int wr, int wc, int fr, int fq) const {
;     ...
;                 bf16_t* base = dst + (size_t)row0 * ldc + colt + cl;
; #pragma unroll
;                 for (int ai = 0; ai < 2; ++ai)
; #pragma unroll
;                     for (int m = 0; m < 4; ++m)
; #pragma unroll
;                         for (int bj = 0; bj < 2; ++bj) { f32x4 v0 = acc[ai][bj][m][0], v1 = acc[ai][bj][m][1];
;                             if (act) {
; #pragma unroll
;                                 for (int j = 0; j < 4; ++j) { v0[j] = fast_silu(v0[j]); v1[j] = fast_silu(v1[j]); } }
;                             u32x4 w; w.x = cvt_pk_bf16(v0[0], v0[1]); w.y = cvt_pk_bf16(v0[2], v0[3]); w.z = cvt_pk_bf16(v1[0], v1[1]); w.w = cvt_pk_bf16(v1[2], v1[3]);
;                             *(u32x4*)(base + (size_t)(ai * 128 + m * 16) * ldc + bj * 128) = w; }
.LBB0_238:
	v_lshl_add_u64 v[148:149], v[148:149], 0, s[66:67]
	v_cvt_pk_bf16_f32 v154, v154, v155
	v_cvt_pk_bf16_f32 v155, v150, v151
	v_cvt_pk_bf16_f32 v156, v156, v157
	v_cvt_pk_bf16_f32 v157, v152, v153
	global_store_dwordx4 v[148:149], v[154:157], off
	s_and_b64 vcc, exec, s[4:5]
	s_cbranch_vccz .Lsilu_7
	v_mov_b32_e32 v150, v76
	v_mov_b32_e32 v151, v77
	v_mov_b32_e32 v152, v68
	v_mov_b32_e32 v153, v69
	v_mov_b32_e32 v154, v74
	v_mov_b32_e32 v155, v75
	v_mov_b32_e32 v156, v66
	v_mov_b32_e32 v157, v67
	s_branch .LBB0_240
.Lsilu_7:
	v_pk_mul_f32 v[150:151], v[76:77], s[100:101]
	v_pk_mul_f32 v[152:153], v[68:69], s[100:101]
	v_pk_mul_f32 v[154:155], v[74:75], s[100:101]
	v_pk_mul_f32 v[156:157], v[66:67], s[100:101]
	v_exp_f32_e32 v150, v150
	v_exp_f32_e32 v151, v151
	v_exp_f32_e32 v152, v152
	v_exp_f32_e32 v153, v153
	v_exp_f32_e32 v154, v154
	v_exp_f32_e32 v155, v155
	v_exp_f32_e32 v156, v156
	v_exp_f32_e32 v157, v157
	v_pk_add_f32 v[150:151], v[150:151], s[98:99]
	v_pk_add_f32 v[152:153], v[152:153], s[98:99]
	v_pk_add_f32 v[154:155], v[154:155], s[98:99]
	v_pk_add_f32 v[156:157], v[156:157], s[98:99]
	v_rcp_f32_e32 v150, v150
	v_rcp_f32_e32 v151, v151
	v_rcp_f32_e32 v152, v152
	v_rcp_f32_e32 v153, v153
	v_rcp_f32_e32 v154, v154
	v_rcp_f32_e32 v155, v155
	v_rcp_f32_e32 v156, v156
	v_rcp_f32_e32 v157, v157
	v_pk_mul_f32 v[150:151], v[76:77], v[150:151]
	v_pk_mul_f32 v[152:153], v[68:69], v[152:153]
	v_pk_mul_f32 v[154:155], v[74:75], v[154:155]
	v_pk_mul_f32 v[156:157], v[66:67], v[156:157]
.LBB0_240:
	v_cvt_pk_bf16_f32 v154, v154, v155
	v_cvt_pk_bf16_f32 v155, v150, v151
	s_nop 0
	v_cvt_pk_bf16_f32 v156, v156, v157
	v_cvt_pk_bf16_f32 v157, v152, v153
	global_store_dwordx4 v[148:149], v[154:157], off offset:256
	s_and_b64 vcc, exec, s[4:5]
	s_cbranch_vccz .Lsilu_8
	v_mov_b32_e32 v150, v64
	v_mov_b32_e32 v151, v65
	v_mov_b32_e32 v152, v56
	v_mov_b32_e32 v153, v57
	v_mov_b32_e32 v154, v62
	v_mov_b32_e32 v155, v63
	v_mov_b32_e32 v156, v54
	v_mov_b32_e32 v157, v55
	s_branch .LBB0_242
.Lsilu_8:
	v_pk_mul_f32 v[150:151], v[64:65], s[100:101]
	v_pk_mul_f32 v[152:153], v[56:57], s[100:101]
	v_pk_mul_f32 v[154:155], v[62:63], s[100:101]
	v_pk_mul_f32 v[156:157], v[54:55], s[100:101]
	v_exp_f32_e32 v150, v150
	v_exp_f32_e32 v151, v151
	v_exp_f32_e32 v152, v152
	v_exp_f32_e32 v153, v153
	v_exp_f32_e32 v154, v154
	v_exp_f32_e32 v155, v155
	v_exp_f32_e32 v156, v156
	v_exp_f32_e32 v157, v157
	v_pk_add_f32 v[150:151], v[150:151], s[98:99]
	v_pk_add_f32 v[152:153], v[152:153], s[98:99]
	v_pk_add_f32 v[154:155], v[154:155], s[98:99]
	v_pk_add_f32 v[156:157], v[156:157], s[98:99]
	v_rcp_f32_e32 v150, v150
	v_rcp_f32_e32 v151, v151
	v_rcp_f32_e32 v152, v152
	v_rcp_f32_e32 v153, v153
	v_rcp_f32_e32 v154, v154
	v_rcp_f32_e32 v155, v155
	v_rcp_f32_e32 v156, v156
	v_rcp_f32_e32 v157, v157
	v_pk_mul_f32 v[150:151], v[64:65], v[150:151]
	v_pk_mul_f32 v[152:153], v[56:57], v[152:153]
	v_pk_mul_f32 v[154:155], v[62:63], v[154:155]
	v_pk_mul_f32 v[156:157], v[54:55], v[156:157]
.LBB0_242:
	s_mul_i32 s6, s68, 0xa0
	v_lshl_add_u64 v[148:149], v[148:149], 0, s[6:7]
	v_cvt_pk_bf16_f32 v154, v154, v155
	v_cvt_pk_bf16_f32 v155, v150, v151
	v_cvt_pk_bf16_f32 v156, v156, v157
	v_cvt_pk_bf16_f32 v157, v152, v153
	global_store_dwordx4 v[148:149], v[154:157], off
	s_and_b64 vcc, exec, s[4:5]
	s_cbranch_vccz .Lsilu_9
	v_mov_b32_e32 v150, v60
	v_mov_b32_e32 v151, v61
	v_mov_b32_e32 v152, v52
	v_mov_b32_e32 v153, v53
	v_mov_b32_e32 v154, v58
	v_mov_b32_e32 v155, v59
	v_mov_b32_e32 v156, v50
	v_mov_b32_e32 v157, v51
	s_branch .LBB0_244
.Lsilu_9:
	v_pk_mul_f32 v[150:151], v[60:61], s[100:101]
	v_pk_mul_f32 v[152:153], v[52:53], s[100:101]
	v_pk_mul_f32 v[154:155], v[58:59], s[100:101]
	v_pk_mul_f32 v[156:157], v[50:51], s[100:101]
	v_exp_f32_e32 v150, v150
	v_exp_f32_e32 v151, v151
	v_exp_f32_e32 v152, v152
	v_exp_f32_e32 v153, v153
	v_exp_f32_e32 v154, v154
	v_exp_f32_e32 v155, v155
	v_exp_f32_e32 v156, v156
	v_exp_f32_e32 v157, v157
	v_pk_add_f32 v[150:151], v[150:151], s[98:99]
	v_pk_add_f32 v[152:153], v[152:153], s[98:99]
	v_pk_add_f32 v[154:155], v[154:155], s[98:99]
	v_pk_add_f32 v[156:157], v[156:157], s[98:99]
	v_rcp_f32_e32 v150, v150
	v_rcp_f32_e32 v151, v151
	v_rcp_f32_e32 v152, v152
	v_rcp_f32_e32 v153, v153
	v_rcp_f32_e32 v154, v154
	v_rcp_f32_e32 v155, v155
	v_rcp_f32_e32 v156, v156
	v_rcp_f32_e32 v157, v157
	v_pk_mul_f32 v[150:151], v[60:61], v[150:151]
	v_pk_mul_f32 v[152:153], v[52:53], v[152:153]
	v_pk_mul_f32 v[154:155], v[58:59], v[154:155]
	v_pk_mul_f32 v[156:157], v[50:51], v[156:157]
.LBB0_244:
	v_cvt_pk_bf16_f32 v154, v154, v155
	v_cvt_pk_bf16_f32 v155, v150, v151
	s_nop 0
	v_cvt_pk_bf16_f32 v156, v156, v157
	v_cvt_pk_bf16_f32 v157, v152, v153
	global_store_dwordx4 v[148:149], v[154:157], off offset:256
	s_and_b64 vcc, exec, s[4:5]
	s_cbranch_vccz .Lsilu_10
	v_mov_b32_e32 v150, v48
	v_mov_b32_e32 v151, v49
	v_mov_b32_e32 v152, v40
	v_mov_b32_e32 v153, v41
	v_mov_b32_e32 v154, v46
	v_mov_b32_e32 v155, v47
	v_mov_b32_e32 v156, v38
	v_mov_b32_e32 v157, v39
	s_branch .LBB0_246
.Lsilu_10:
	v_pk_mul_f32 v[150:151], v[48:49], s[100:101]
	v_pk_mul_f32 v[152:153], v[40:41], s[100:101]
	v_pk_mul_f32 v[154:155], v[46:47], s[100:101]
	v_pk_mul_f32 v[156:157], v[38:39], s[100:101]
	v_exp_f32_e32 v150, v150
	v_exp_f32_e32 v151, v151
	v_exp_f32_e32 v152, v152
	v_exp_f32_e32 v153, v153
	v_exp_f32_e32 v154, v154
	v_exp_f32_e32 v155, v155
	v_exp_f32_e32 v156, v156
	v_exp_f32_e32 v157, v157
	v_pk_add_f32 v[150:151], v[150:151], s[98:99]
	v_pk_add_f32 v[152:153], v[152:153], s[98:99]
	v_pk_add_f32 v[154:155], v[154:155], s[98:99]
	v_pk_add_f32 v[156:157], v[156:157], s[98:99]
	v_rcp_f32_e32 v150, v150
	v_rcp_f32_e32 v151, v151
	v_rcp_f32_e32 v152, v152
	v_rcp_f32_e32 v153, v153
	v_rcp_f32_e32 v154, v154
	v_rcp_f32_e32 v155, v155
	v_rcp_f32_e32 v156, v156
	v_rcp_f32_e32 v157, v157
	v_pk_mul_f32 v[150:151], v[48:49], v[150:151]
	v_pk_mul_f32 v[152:153], v[40:41], v[152:153]
	v_pk_mul_f32 v[154:155], v[46:47], v[154:155]
	v_pk_mul_f32 v[156:157], v[38:39], v[156:157]
; __device__ __forceinline__ unsigned cvt_pk_bf16(float lo, float hi) { unsigned r; asm volatile("v_cvt_pk_bf16_f32 %0, %1, %2" : "=v"(r) : "v"(lo), "v"(hi)); return r; }
; __device__ __forceinline__ float fast_silu(float x) { return x * fast_sigmoid(x); }
;     __device__ __forceinline__ void operator()(const f32x4 (&acc)[2][2][4][2], const Unit& u, int wr, int wc, int fr, int fq) const {
;     ...
;                 bf16_t* base = dst + (size_t)row0 * ldc + colt + cl;
; #pragma unroll
;                 for (int ai = 0; ai < 2; ++ai)
; #pragma unroll
;                     for (int m = 0; m < 4; ++m)
; #pragma unroll
;                         for (int bj = 0; bj < 2; ++bj) { f32x4 v0 = acc[ai][bj][m][0], v1 = acc[ai][bj][m][1];
;                             if (act) {
; #pragma unroll
;                                 for (int j = 0; j < 4; ++j) { v0[j] = fast_silu(v0[j]); v1[j] = fast_silu(v1[j]); } }
;                             u32x4 w; w.x = cvt_pk_bf16(v0[0], v0[1]); w.y = cvt_pk_bf16(v0[2], v0[3]); w.z = cvt_pk_bf16(v1[0], v1[1]); w.w = cvt_pk_bf16(v1[2], v1[3]);
;                             *(u32x4*)(base + (size_t)(ai * 128 + m * 16) * ldc + bj * 128) = w; }
.LBB0_246:
	v_lshl_add_u64 v[148:149], v[148:149], 0, s[66:67]
	v_cvt_pk_bf16_f32 v154, v154, v155
	v_cvt_pk_bf16_f32 v155, v150, v151
	v_cvt_pk_bf16_f32 v156, v156, v157
	v_cvt_pk_bf16_f32 v157, v152, v153
	global_store_dwordx4 v[148:149], v[154:157], off
	s_and_b64 vcc, exec, s[4:5]
	s_cbranch_vccz .Lsilu_11
	v_mov_b32_e32 v150, v44
	v_mov_b32_e32 v151, v45
	v_mov_b32_e32 v152, v36
	v_mov_b32_e32 v153, v37
	v_mov_b32_e32 v154, v42
	v_mov_b32_e32 v155, v43
	v_mov_b32_e32 v156, v34
	v_mov_b32_e32 v157, v35
	s_branch .LBB0_248
.Lsilu_11:
	v_pk_mul_f32 v[150:151], v[44:45], s[100:101]
	v_pk_mul_f32 v[152:153], v[36:37], s[100:101]
	v_pk_mul_f32 v[154:155], v[42:43], s[100:101]
	v_pk_mul_f32 v[156:157], v[34:35], s[100:101]
	v_exp_f32_e32 v150, v150
	v_exp_f32_e32 v151, v151
	v_exp_f32_e32 v152, v152
	v_exp_f32_e32 v153, v153
	v_exp_f32_e32 v154, v154
	v_exp_f32_e32 v155, v155
	v_exp_f32_e32 v156, v156
	v_exp_f32_e32 v157, v157
	v_pk_add_f32 v[150:151], v[150:151], s[98:99]
	v_pk_add_f32 v[152:153], v[152:153], s[98:99]
	v_pk_add_f32 v[154:155], v[154:155], s[98:99]
	v_pk_add_f32 v[156:157], v[156:157], s[98:99]
	v_rcp_f32_e32 v150, v150
	v_rcp_f32_e32 v151, v151
	v_rcp_f32_e32 v152, v152
	v_rcp_f32_e32 v153, v153
	v_rcp_f32_e32 v154, v154
	v_rcp_f32_e32 v155, v155
	v_rcp_f32_e32 v156, v156
	v_rcp_f32_e32 v157, v157
	v_pk_mul_f32 v[150:151], v[44:45], v[150:151]
	v_pk_mul_f32 v[152:153], v[36:37], v[152:153]
	v_pk_mul_f32 v[154:155], v[42:43], v[154:155]
	v_pk_mul_f32 v[156:157], v[34:35], v[156:157]
.LBB0_248:
	v_cvt_pk_bf16_f32 v154, v154, v155
	v_cvt_pk_bf16_f32 v155, v150, v151
	s_nop 0
	v_cvt_pk_bf16_f32 v156, v156, v157
	v_cvt_pk_bf16_f32 v157, v152, v153
	global_store_dwordx4 v[148:149], v[154:157], off offset:256
	s_and_b64 vcc, exec, s[4:5]
	s_cbranch_vccz .Lsilu_12
	v_mov_b32_e32 v150, v32
	v_mov_b32_e32 v151, v33
	v_mov_b32_e32 v152, v24
	v_mov_b32_e32 v153, v25
	v_mov_b32_e32 v154, v30
	v_mov_b32_e32 v155, v31
	v_mov_b32_e32 v156, v22
	v_mov_b32_e32 v157, v23
	s_branch .LBB0_250
.Lsilu_12:
	v_pk_mul_f32 v[150:151], v[32:33], s[100:101]
	v_pk_mul_f32 v[152:153], v[24:25], s[100:101]
	v_pk_mul_f32 v[154:155], v[30:31], s[100:101]
	v_pk_mul_f32 v[156:157], v[22:23], s[100:101]
	v_exp_f32_e32 v150, v150
	v_exp_f32_e32 v151, v151
	v_exp_f32_e32 v152, v152
	v_exp_f32_e32 v153, v153
	v_exp_f32_e32 v154, v154
	v_exp_f32_e32 v155, v155
	v_exp_f32_e32 v156, v156
	v_exp_f32_e32 v157, v157
	v_pk_add_f32 v[150:151], v[150:151], s[98:99]
	v_pk_add_f32 v[152:153], v[152:153], s[98:99]
	v_pk_add_f32 v[154:155], v[154:155], s[98:99]
	v_pk_add_f32 v[156:157], v[156:157], s[98:99]
	v_rcp_f32_e32 v150, v150
	v_rcp_f32_e32 v151, v151
	v_rcp_f32_e32 v152, v152
	v_rcp_f32_e32 v153, v153
	v_rcp_f32_e32 v154, v154
	v_rcp_f32_e32 v155, v155
	v_rcp_f32_e32 v156, v156
	v_rcp_f32_e32 v157, v157
	v_pk_mul_f32 v[150:151], v[32:33], v[150:151]
	v_pk_mul_f32 v[152:153], v[24:25], v[152:153]
	v_pk_mul_f32 v[154:155], v[30:31], v[154:155]
	v_pk_mul_f32 v[156:157], v[22:23], v[156:157]
.LBB0_250:
	v_lshl_add_u64 v[148:149], v[148:149], 0, s[66:67]
	v_cvt_pk_bf16_f32 v154, v154, v155
	v_cvt_pk_bf16_f32 v155, v150, v151
	v_cvt_pk_bf16_f32 v156, v156, v157
	v_cvt_pk_bf16_f32 v157, v152, v153
	global_store_dwordx4 v[148:149], v[154:157], off
	s_and_b64 vcc, exec, s[4:5]
	s_cbranch_vccz .Lsilu_13
	v_mov_b32_e32 v150, v28
	v_mov_b32_e32 v151, v29
	v_mov_b32_e32 v152, v20
	v_mov_b32_e32 v153, v21
	v_mov_b32_e32 v154, v26
	v_mov_b32_e32 v155, v27
	v_mov_b32_e32 v156, v18
	v_mov_b32_e32 v157, v19
	s_branch .LBB0_252
; __device__ __forceinline__ unsigned cvt_pk_bf16(float lo, float hi) { unsigned r; asm volatile("v_cvt_pk_bf16_f32 %0, %1, %2" : "=v"(r) : "v"(lo), "v"(hi)); return r; }
; __device__ __forceinline__ float fast_silu(float x) { return x * fast_sigmoid(x); }
;     __device__ __forceinline__ void operator()(const f32x4 (&acc)[2][2][4][2], const Unit& u, int wr, int wc, int fr, int fq) const {
;     ...
;                 bf16_t* base = dst + (size_t)row0 * ldc + colt + cl;
; #pragma unroll
;                 for (int ai = 0; ai < 2; ++ai)
; #pragma unroll
;                     for (int m = 0; m < 4; ++m)
; #pragma unroll
;                         for (int bj = 0; bj < 2; ++bj) { f32x4 v0 = acc[ai][bj][m][0], v1 = acc[ai][bj][m][1];
;                             if (act) {
; #pragma unroll
;                                 for (int j = 0; j < 4; ++j) { v0[j] = fast_silu(v0[j]); v1[j] = fast_silu(v1[j]); } }
;                             u32x4 w; w.x = cvt_pk_bf16(v0[0], v0[1]); w.y = cvt_pk_bf16(v0[2], v0[3]); w.z = cvt_pk_bf16(v1[0], v1[1]); w.w = cvt_pk_bf16(v1[2], v1[3]);
;                             *(u32x4*)(base + (size_t)(ai * 128 + m * 16) * ldc + bj * 128) = w; }
.Lsilu_13:
	v_pk_mul_f32 v[150:151], v[28:29], s[100:101]
	v_pk_mul_f32 v[152:153], v[20:21], s[100:101]
	v_pk_mul_f32 v[154:155], v[26:27], s[100:101]
	v_pk_mul_f32 v[156:157], v[18:19], s[100:101]
	v_exp_f32_e32 v150, v150
	v_exp_f32_e32 v151, v151
	v_exp_f32_e32 v152, v152
	v_exp_f32_e32 v153, v153
	v_exp_f32_e32 v154, v154
	v_exp_f32_e32 v155, v155
	v_exp_f32_e32 v156, v156
	v_exp_f32_e32 v157, v157
	v_pk_add_f32 v[150:151], v[150:151], s[98:99]
	v_pk_add_f32 v[152:153], v[152:153], s[98:99]
	v_pk_add_f32 v[154:155], v[154:155], s[98:99]
	v_pk_add_f32 v[156:157], v[156:157], s[98:99]
	v_rcp_f32_e32 v150, v150
	v_rcp_f32_e32 v151, v151
	v_rcp_f32_e32 v152, v152
	v_rcp_f32_e32 v153, v153
	v_rcp_f32_e32 v154, v154
	v_rcp_f32_e32 v155, v155
	v_rcp_f32_e32 v156, v156
	v_rcp_f32_e32 v157, v157
	v_pk_mul_f32 v[150:151], v[28:29], v[150:151]
	v_pk_mul_f32 v[152:153], v[20:21], v[152:153]
	v_pk_mul_f32 v[154:155], v[26:27], v[154:155]
	v_pk_mul_f32 v[156:157], v[18:19], v[156:157]
.LBB0_252:
	v_cvt_pk_bf16_f32 v154, v154, v155
	v_cvt_pk_bf16_f32 v155, v150, v151
	s_nop 0
	v_cvt_pk_bf16_f32 v156, v156, v157
	v_cvt_pk_bf16_f32 v157, v152, v153
	global_store_dwordx4 v[148:149], v[154:157], off offset:256
	s_and_b64 vcc, exec, s[4:5]
	s_cbranch_vccz .Lsilu_14
	v_mov_b32_e32 v150, v16
	v_mov_b32_e32 v151, v17
	v_mov_b32_e32 v152, v8
	v_mov_b32_e32 v153, v9
	v_mov_b32_e32 v154, v14
	v_mov_b32_e32 v155, v15
	v_mov_b32_e32 v156, v6
	v_mov_b32_e32 v157, v7
	s_branch .LBB0_254
.Lsilu_14:
	v_pk_mul_f32 v[150:151], v[16:17], s[100:101]
	v_pk_mul_f32 v[152:153], v[8:9], s[100:101]
	v_pk_mul_f32 v[154:155], v[14:15], s[100:101]
	v_pk_mul_f32 v[156:157], v[6:7], s[100:101]
	v_exp_f32_e32 v150, v150
	v_exp_f32_e32 v151, v151
	v_exp_f32_e32 v152, v152
	v_exp_f32_e32 v153, v153
	v_exp_f32_e32 v154, v154
	v_exp_f32_e32 v155, v155
	v_exp_f32_e32 v156, v156
	v_exp_f32_e32 v157, v157
	v_pk_add_f32 v[150:151], v[150:151], s[98:99]
	v_pk_add_f32 v[152:153], v[152:153], s[98:99]
	v_pk_add_f32 v[154:155], v[154:155], s[98:99]
	v_pk_add_f32 v[156:157], v[156:157], s[98:99]
	v_rcp_f32_e32 v150, v150
	v_rcp_f32_e32 v151, v151
	v_rcp_f32_e32 v152, v152
	v_rcp_f32_e32 v153, v153
	v_rcp_f32_e32 v154, v154
	v_rcp_f32_e32 v155, v155
	v_rcp_f32_e32 v156, v156
	v_rcp_f32_e32 v157, v157
	v_pk_mul_f32 v[150:151], v[16:17], v[150:151]
	v_pk_mul_f32 v[152:153], v[8:9], v[152:153]
	v_pk_mul_f32 v[154:155], v[14:15], v[154:155]
	v_pk_mul_f32 v[156:157], v[6:7], v[156:157]
.LBB0_254:
	v_lshl_add_u64 v[148:149], v[148:149], 0, s[66:67]
	v_cvt_pk_bf16_f32 v154, v154, v155
	v_cvt_pk_bf16_f32 v155, v150, v151
	v_cvt_pk_bf16_f32 v156, v156, v157
	v_cvt_pk_bf16_f32 v157, v152, v153
	global_store_dwordx4 v[148:149], v[154:157], off
	s_and_b64 vcc, exec, s[4:5]
	s_cbranch_vccz .Lsilu_15
	v_mov_b32_e32 v150, v4
	v_mov_b32_e32 v151, v5
	v_mov_b32_e32 v152, v12
	v_mov_b32_e32 v153, v13
	v_mov_b32_e32 v154, v2
	v_mov_b32_e32 v155, v3
	v_mov_b32_e32 v156, v10
	v_mov_b32_e32 v157, v11
	s_branch .LBB0_256
.Lsilu_15:
	v_pk_mul_f32 v[150:151], v[4:5], s[100:101]
	v_pk_mul_f32 v[152:153], v[12:13], s[100:101]
	v_pk_mul_f32 v[154:155], v[2:3], s[100:101]
	v_pk_mul_f32 v[156:157], v[10:11], s[100:101]
	v_exp_f32_e32 v150, v150
	v_exp_f32_e32 v151, v151
	v_exp_f32_e32 v152, v152
	v_exp_f32_e32 v153, v153
	v_exp_f32_e32 v154, v154
	v_exp_f32_e32 v155, v155
	v_exp_f32_e32 v156, v156
	v_exp_f32_e32 v157, v157
	v_pk_add_f32 v[150:151], v[150:151], s[98:99]
	v_pk_add_f32 v[152:153], v[152:153], s[98:99]
	v_pk_add_f32 v[154:155], v[154:155], s[98:99]
	v_pk_add_f32 v[156:157], v[156:157], s[98:99]
	v_rcp_f32_e32 v150, v150
	v_rcp_f32_e32 v151, v151
	v_rcp_f32_e32 v152, v152
	v_rcp_f32_e32 v153, v153
	v_rcp_f32_e32 v154, v154
	v_rcp_f32_e32 v155, v155
	v_rcp_f32_e32 v156, v156
	v_rcp_f32_e32 v157, v157
	v_pk_mul_f32 v[150:151], v[4:5], v[150:151]
	v_pk_mul_f32 v[152:153], v[12:13], v[152:153]
	v_pk_mul_f32 v[154:155], v[2:3], v[154:155]
	v_pk_mul_f32 v[156:157], v[10:11], v[156:157]
